# barrier poll loops sleep 8 instead of 1 between polls (fewer pollers' loads competing with the stragglers)
# baseline (speedup 1.0000x reference)
.LBB0_11:
	global_load_dword v16, v17, s[8:9] sc1
	s_waitcnt lgkmcnt(0)
	global_load_dword v1, v17, s[10:11] sc1
	global_load_dword v2, v17, s[12:13] sc1
	global_load_dword v3, v17, s[14:15] sc1
	global_load_dword v4, v17, s[16:17] sc1
	global_load_dword v5, v17, s[18:19] sc1
	global_load_dword v6, v17, s[20:21] sc1
	global_load_dword v7, v17, s[22:23] sc1
	global_load_dword v8, v17, s[24:25] sc1
	global_load_dword v9, v17, s[26:27] sc1
	global_load_dword v10, v17, s[28:29] sc1
	global_load_dword v11, v17, s[30:31] sc1
	global_load_dword v12, v17, s[34:35] sc1
	global_load_dword v13, v17, s[36:37] sc1
	global_load_dword v14, v17, s[38:39] sc1
	global_load_dword v15, v17, s[40:41] sc1
	s_mov_b64 s[42:43], -1
	s_mov_b64 s[84:85], -1
	s_waitcnt vmcnt(14)
	v_add_u32_e32 v18, v1, v16
	s_waitcnt vmcnt(13)
	v_add_u32_e32 v18, v18, v2
	s_waitcnt vmcnt(12)
	v_add_u32_e32 v18, v18, v3
	s_waitcnt vmcnt(11)
	v_add_u32_e32 v18, v18, v4
	s_waitcnt vmcnt(10)
	v_add_u32_e32 v18, v18, v5
	s_waitcnt vmcnt(9)
	v_add_u32_e32 v18, v18, v6
	s_waitcnt vmcnt(8)
	v_add_u32_e32 v18, v18, v7
	s_waitcnt vmcnt(7)
	v_add_u32_e32 v18, v18, v8
	s_waitcnt vmcnt(6)
	v_add_u32_e32 v18, v18, v9
	s_waitcnt vmcnt(5)
	v_add_u32_e32 v18, v18, v10
	s_waitcnt vmcnt(4)
	v_add_u32_e32 v18, v18, v11
	s_waitcnt vmcnt(3)
	v_add_u32_e32 v18, v18, v12
	s_waitcnt vmcnt(2)
	v_add_u32_e32 v18, v18, v13
	s_waitcnt vmcnt(1)
	v_add_u32_e32 v18, v18, v14
	s_waitcnt vmcnt(0)
	v_add_u32_e32 v18, v18, v15
	v_cmp_eq_u32_e32 vcc, s46, v18
	s_cbranch_vccnz .LBB0_10
	s_and_b32 s42, s47, 0xff
	s_cmp_eq_u32 s42, 0
	s_mov_b64 s[42:43], -1
	s_mov_b64 s[86:87], -1
	s_sleep 8
	s_cbranch_scc1 .LBB0_15
	s_and_b64 vcc, exec, s[86:87]
	s_cbranch_vccz .LBB0_10

.LBB0_29:
	s_and_b32 s22, s26, 0xff
	s_mov_b64 s[20:21], -1
	s_cmp_lg_u32 s22, 0
	s_mov_b64 s[24:25], -1
	s_sleep 8
	s_cbranch_scc0 .LBB0_32
	s_and_b64 vcc, exec, s[24:25]
	s_cbranch_vccz .LBB0_28

.LBB0_46:
	s_and_b32 s20, s26, 0xff
	s_cmp_lg_u32 s20, 0
	s_mov_b64 s[22:23], -1
	s_sleep 8
	s_cbranch_scc0 .LBB0_49
	s_mov_b64 s[24:25], -1
	s_and_b64 vcc, exec, s[22:23]
	s_cbranch_vccz .LBB0_45

.LBB0_130:
	global_load_dword v16, v17, s[8:9] sc1
	s_waitcnt lgkmcnt(0)
	global_load_dword v1, v17, s[10:11] sc1
	global_load_dword v2, v17, s[12:13] sc1
	global_load_dword v3, v17, s[14:15] sc1
	global_load_dword v4, v17, s[16:17] sc1
	global_load_dword v5, v17, s[18:19] sc1
	global_load_dword v6, v17, s[20:21] sc1
	global_load_dword v7, v17, s[22:23] sc1
	global_load_dword v8, v17, s[24:25] sc1
	global_load_dword v9, v17, s[26:27] sc1
	global_load_dword v10, v17, s[28:29] sc1
	global_load_dword v11, v17, s[30:31] sc1
	global_load_dword v12, v17, s[34:35] sc1
	global_load_dword v13, v17, s[36:37] sc1
	global_load_dword v14, v17, s[38:39] sc1
	global_load_dword v15, v17, s[40:41] sc1
	s_mov_b64 s[42:43], -1
	s_mov_b64 s[66:67], -1
	s_waitcnt vmcnt(14)
	v_add_u32_e32 v18, v1, v16
	s_waitcnt vmcnt(13)
	v_add_u32_e32 v18, v18, v2
	s_waitcnt vmcnt(12)
	v_add_u32_e32 v18, v18, v3
	s_waitcnt vmcnt(11)
	v_add_u32_e32 v18, v18, v4
	s_waitcnt vmcnt(10)
	v_add_u32_e32 v18, v18, v5
	s_waitcnt vmcnt(9)
	v_add_u32_e32 v18, v18, v6
	s_waitcnt vmcnt(8)
	v_add_u32_e32 v18, v18, v7
	s_waitcnt vmcnt(7)
	v_add_u32_e32 v18, v18, v8
	s_waitcnt vmcnt(6)
	v_add_u32_e32 v18, v18, v9
	s_waitcnt vmcnt(5)
	v_add_u32_e32 v18, v18, v10
	s_waitcnt vmcnt(4)
	v_add_u32_e32 v18, v18, v11
	s_waitcnt vmcnt(3)
	v_add_u32_e32 v18, v18, v12
	s_waitcnt vmcnt(2)
	v_add_u32_e32 v18, v18, v13
	s_waitcnt vmcnt(1)
	v_add_u32_e32 v18, v18, v14
	s_waitcnt vmcnt(0)
	v_add_u32_e32 v18, v18, v15
	v_cmp_eq_u32_e32 vcc, s46, v18
	s_cbranch_vccnz .LBB0_129
	s_and_b32 s42, s47, 0xff
	s_cmp_eq_u32 s42, 0
	s_mov_b64 s[42:43], -1
	s_mov_b64 s[68:69], -1
	s_sleep 8
	s_cbranch_scc1 .LBB0_134
	s_and_b64 vcc, exec, s[68:69]
	s_cbranch_vccz .LBB0_129

.LBB0_148:
	s_and_b32 s20, s24, 0xff
	s_mov_b64 s[18:19], -1
	s_cmp_lg_u32 s20, 0
	s_mov_b64 s[22:23], -1
	s_sleep 8
	s_cbranch_scc0 .LBB0_151
	s_and_b64 vcc, exec, s[22:23]
	s_cbranch_vccz .LBB0_147

.LBB0_382:
	global_load_dword v16, v17, s[4:5] sc1
	s_waitcnt lgkmcnt(0)
	global_load_dword v1, v17, s[8:9] sc1
	global_load_dword v2, v17, s[10:11] sc1
	global_load_dword v3, v17, s[12:13] sc1
	global_load_dword v4, v17, s[14:15] sc1
	global_load_dword v5, v17, s[16:17] sc1
	global_load_dword v6, v17, s[18:19] sc1
	global_load_dword v7, v17, s[20:21] sc1
	global_load_dword v8, v17, s[22:23] sc1
	global_load_dword v9, v17, s[24:25] sc1
	global_load_dword v10, v17, s[26:27] sc1
	global_load_dword v11, v17, s[28:29] sc1
	global_load_dword v12, v17, s[30:31] sc1
	global_load_dword v13, v17, s[34:35] sc1
	global_load_dword v14, v17, s[36:37] sc1
	global_load_dword v15, v17, s[38:39] sc1
	s_mov_b64 s[40:41], -1
	s_mov_b64 s[42:43], -1
	s_waitcnt vmcnt(14)
	v_add_u32_e32 v18, v1, v16
	s_waitcnt vmcnt(13)
	v_add_u32_e32 v18, v18, v2
	s_waitcnt vmcnt(12)
	v_add_u32_e32 v18, v18, v3
	s_waitcnt vmcnt(11)
	v_add_u32_e32 v18, v18, v4
	s_waitcnt vmcnt(10)
	v_add_u32_e32 v18, v18, v5
	s_waitcnt vmcnt(9)
	v_add_u32_e32 v18, v18, v6
	s_waitcnt vmcnt(8)
	v_add_u32_e32 v18, v18, v7
	s_waitcnt vmcnt(7)
	v_add_u32_e32 v18, v18, v8
	s_waitcnt vmcnt(6)
	v_add_u32_e32 v18, v18, v9
	s_waitcnt vmcnt(5)
	v_add_u32_e32 v18, v18, v10
	s_waitcnt vmcnt(4)
	v_add_u32_e32 v18, v18, v11
	s_waitcnt vmcnt(3)
	v_add_u32_e32 v18, v18, v12
	s_waitcnt vmcnt(2)
	v_add_u32_e32 v18, v18, v13
	s_waitcnt vmcnt(1)
	v_add_u32_e32 v18, v18, v14
	s_waitcnt vmcnt(0)
	v_add_u32_e32 v18, v18, v15
	v_cmp_eq_u32_e32 vcc, s46, v18
	s_cbranch_vccnz .LBB0_381
	s_and_b32 s40, s47, 0xff
	s_cmp_eq_u32 s40, 0
	s_mov_b64 s[40:41], -1
	s_mov_b64 s[50:51], -1
	s_sleep 8
	s_cbranch_scc1 .LBB0_386
	s_and_b64 vcc, exec, s[50:51]
	s_cbranch_vccz .LBB0_381

.LBB0_400:
	s_and_b32 s18, s22, 0xff
	s_mov_b64 s[16:17], -1
	s_cmp_lg_u32 s18, 0
	s_mov_b64 s[20:21], -1
	s_sleep 8
	s_cbranch_scc0 .LBB0_403
	s_and_b64 vcc, exec, s[20:21]
	s_cbranch_vccz .LBB0_399

.LBB0_417:
	s_and_b32 s18, s24, 0xff
	s_cmp_lg_u32 s18, 0
	s_mov_b64 s[20:21], -1
	s_sleep 8
	s_cbranch_scc0 .LBB0_420
	s_mov_b64 s[22:23], -1
	s_and_b64 vcc, exec, s[20:21]
	s_cbranch_vccz .LBB0_416

.LBB0_520:
	global_load_dword v16, v17, s[4:5] sc1
	s_waitcnt lgkmcnt(0)
	global_load_dword v1, v17, s[6:7] sc1
	global_load_dword v2, v17, s[8:9] sc1
	global_load_dword v3, v17, s[10:11] sc1
	global_load_dword v4, v17, s[12:13] sc1
	global_load_dword v5, v17, s[14:15] sc1
	global_load_dword v6, v17, s[16:17] sc1
	global_load_dword v7, v17, s[18:19] sc1
	global_load_dword v8, v17, s[20:21] sc1
	global_load_dword v9, v17, s[22:23] sc1
	global_load_dword v10, v17, s[24:25] sc1
	global_load_dword v11, v17, s[26:27] sc1
	global_load_dword v12, v17, s[28:29] sc1
	global_load_dword v13, v17, s[30:31] sc1
	global_load_dword v14, v17, s[34:35] sc1
	global_load_dword v15, v17, s[36:37] sc1
	s_mov_b64 s[38:39], -1
	s_mov_b64 s[40:41], -1
	s_waitcnt vmcnt(14)
	v_add_u32_e32 v18, v1, v16
	s_waitcnt vmcnt(13)
	v_add_u32_e32 v18, v18, v2
	s_waitcnt vmcnt(12)
	v_add_u32_e32 v18, v18, v3
	s_waitcnt vmcnt(11)
	v_add_u32_e32 v18, v18, v4
	s_waitcnt vmcnt(10)
	v_add_u32_e32 v18, v18, v5
	s_waitcnt vmcnt(9)
	v_add_u32_e32 v18, v18, v6
	s_waitcnt vmcnt(8)
	v_add_u32_e32 v18, v18, v7
	s_waitcnt vmcnt(7)
	v_add_u32_e32 v18, v18, v8
	s_waitcnt vmcnt(6)
	v_add_u32_e32 v18, v18, v9
	s_waitcnt vmcnt(5)
	v_add_u32_e32 v18, v18, v10
	s_waitcnt vmcnt(4)
	v_add_u32_e32 v18, v18, v11
	s_waitcnt vmcnt(3)
	v_add_u32_e32 v18, v18, v12
	s_waitcnt vmcnt(2)
	v_add_u32_e32 v18, v18, v13
	s_waitcnt vmcnt(1)
	v_add_u32_e32 v18, v18, v14
	s_waitcnt vmcnt(0)
	v_add_u32_e32 v18, v18, v15
	v_cmp_eq_u32_e32 vcc, s46, v18
	s_cbranch_vccnz .LBB0_519
	s_and_b32 s38, s47, 0xff
	s_cmp_eq_u32 s38, 0
	s_mov_b64 s[38:39], -1
	s_mov_b64 s[42:43], -1
	s_sleep 8
	s_cbranch_scc1 .LBB0_524
	s_and_b64 vcc, exec, s[42:43]
	s_cbranch_vccz .LBB0_519

.LBB0_555:
	s_and_b32 s16, s22, 0xff
	s_cmp_lg_u32 s16, 0
	s_mov_b64 s[18:19], -1
	s_sleep 8
	s_cbranch_scc0 .LBB0_558
	s_mov_b64 s[20:21], -1
	s_and_b64 vcc, exec, s[18:19]
	s_cbranch_vccz .LBB0_554

.LBB0_667:
	global_load_dword v16, v17, s[6:7] sc1
	s_waitcnt lgkmcnt(0)
	global_load_dword v1, v17, s[8:9] sc1
	global_load_dword v2, v17, s[10:11] sc1
	global_load_dword v3, v17, s[12:13] sc1
	global_load_dword v4, v17, s[14:15] sc1
	global_load_dword v5, v17, s[16:17] sc1
	global_load_dword v6, v17, s[18:19] sc1
	global_load_dword v7, v17, s[20:21] sc1
	global_load_dword v8, v17, s[22:23] sc1
	global_load_dword v9, v17, s[24:25] sc1
	global_load_dword v10, v17, s[26:27] sc1
	global_load_dword v11, v17, s[28:29] sc1
	global_load_dword v12, v17, s[30:31] sc1
	global_load_dword v13, v17, s[34:35] sc1
	global_load_dword v14, v17, s[36:37] sc1
	global_load_dword v15, v17, s[38:39] sc1
	s_mov_b64 s[40:41], -1
	s_mov_b64 s[42:43], -1
	s_waitcnt vmcnt(14)
	v_add_u32_e32 v18, v1, v16
	s_waitcnt vmcnt(13)
	v_add_u32_e32 v18, v18, v2
	s_waitcnt vmcnt(12)
	v_add_u32_e32 v18, v18, v3
	s_waitcnt vmcnt(11)
	v_add_u32_e32 v18, v18, v4
	s_waitcnt vmcnt(10)
	v_add_u32_e32 v18, v18, v5
	s_waitcnt vmcnt(9)
	v_add_u32_e32 v18, v18, v6
	s_waitcnt vmcnt(8)
	v_add_u32_e32 v18, v18, v7
	s_waitcnt vmcnt(7)
	v_add_u32_e32 v18, v18, v8
	s_waitcnt vmcnt(6)
	v_add_u32_e32 v18, v18, v9
	s_waitcnt vmcnt(5)
	v_add_u32_e32 v18, v18, v10
	s_waitcnt vmcnt(4)
	v_add_u32_e32 v18, v18, v11
	s_waitcnt vmcnt(3)
	v_add_u32_e32 v18, v18, v12
	s_waitcnt vmcnt(2)
	v_add_u32_e32 v18, v18, v13
	s_waitcnt vmcnt(1)
	v_add_u32_e32 v18, v18, v14
	s_waitcnt vmcnt(0)
	v_add_u32_e32 v18, v18, v15
	v_cmp_eq_u32_e32 vcc, s46, v18
	s_cbranch_vccnz .LBB0_666
	s_and_b32 s40, s47, 0xff
	s_cmp_eq_u32 s40, 0
	s_mov_b64 s[40:41], -1
	s_mov_b64 s[48:49], -1
	s_sleep 8
	s_cbranch_scc1 .LBB0_671
	s_and_b64 vcc, exec, s[48:49]
	s_cbranch_vccz .LBB0_666

.LBB0_762:
	global_load_dword v16, v17, s[4:5] sc1
	s_waitcnt lgkmcnt(0)
	global_load_dword v1, v17, s[8:9] sc1
	global_load_dword v2, v17, s[10:11] sc1
	global_load_dword v3, v17, s[12:13] sc1
	global_load_dword v4, v17, s[14:15] sc1
	global_load_dword v5, v17, s[16:17] sc1
	global_load_dword v6, v17, s[18:19] sc1
	global_load_dword v7, v17, s[20:21] sc1
	global_load_dword v8, v17, s[22:23] sc1
	global_load_dword v9, v17, s[24:25] sc1
	global_load_dword v10, v17, s[26:27] sc1
	global_load_dword v11, v17, s[28:29] sc1
	global_load_dword v12, v17, s[30:31] sc1
	global_load_dword v13, v17, s[34:35] sc1
	global_load_dword v14, v17, s[36:37] sc1
	global_load_dword v15, v17, s[38:39] sc1
	s_mov_b64 s[40:41], -1
	s_mov_b64 s[42:43], -1
	s_waitcnt vmcnt(14)
	v_add_u32_e32 v18, v1, v16
	s_waitcnt vmcnt(13)
	v_add_u32_e32 v18, v18, v2
	s_waitcnt vmcnt(12)
	v_add_u32_e32 v18, v18, v3
	s_waitcnt vmcnt(11)
	v_add_u32_e32 v18, v18, v4
	s_waitcnt vmcnt(10)
	v_add_u32_e32 v18, v18, v5
	s_waitcnt vmcnt(9)
	v_add_u32_e32 v18, v18, v6
	s_waitcnt vmcnt(8)
	v_add_u32_e32 v18, v18, v7
	s_waitcnt vmcnt(7)
	v_add_u32_e32 v18, v18, v8
	s_waitcnt vmcnt(6)
	v_add_u32_e32 v18, v18, v9
	s_waitcnt vmcnt(5)
	v_add_u32_e32 v18, v18, v10
	s_waitcnt vmcnt(4)
	v_add_u32_e32 v18, v18, v11
	s_waitcnt vmcnt(3)
	v_add_u32_e32 v18, v18, v12
	s_waitcnt vmcnt(2)
	v_add_u32_e32 v18, v18, v13
	s_waitcnt vmcnt(1)
	v_add_u32_e32 v18, v18, v14
	s_waitcnt vmcnt(0)
	v_add_u32_e32 v18, v18, v15
	v_cmp_eq_u32_e32 vcc, s46, v18
	s_cbranch_vccnz .LBB0_761
	s_and_b32 s40, s47, 0xff
	s_cmp_eq_u32 s40, 0
	s_mov_b64 s[40:41], -1
	s_mov_b64 s[48:49], -1
	s_sleep 8
	s_cbranch_scc1 .LBB0_766
	s_and_b64 vcc, exec, s[48:49]
	s_cbranch_vccz .LBB0_761

.LBB0_855:
	global_load_dword v16, v17, s[4:5] sc1
	s_waitcnt lgkmcnt(0)
	global_load_dword v1, v17, s[6:7] sc1
	global_load_dword v2, v17, s[8:9] sc1
	global_load_dword v3, v17, s[10:11] sc1
	global_load_dword v4, v17, s[12:13] sc1
	global_load_dword v5, v17, s[14:15] sc1
	global_load_dword v6, v17, s[16:17] sc1
	global_load_dword v7, v17, s[18:19] sc1
	global_load_dword v8, v17, s[20:21] sc1
	global_load_dword v9, v17, s[22:23] sc1
	global_load_dword v10, v17, s[24:25] sc1
	global_load_dword v11, v17, s[26:27] sc1
	global_load_dword v12, v17, s[28:29] sc1
	global_load_dword v13, v17, s[30:31] sc1
	global_load_dword v14, v17, s[34:35] sc1
	global_load_dword v15, v17, s[36:37] sc1
	s_mov_b64 s[38:39], -1
	s_mov_b64 s[40:41], -1
	s_waitcnt vmcnt(14)
	v_add_u32_e32 v18, v1, v16
	s_waitcnt vmcnt(13)
	v_add_u32_e32 v18, v18, v2
	s_waitcnt vmcnt(12)
	v_add_u32_e32 v18, v18, v3
	s_waitcnt vmcnt(11)
	v_add_u32_e32 v18, v18, v4
	s_waitcnt vmcnt(10)
	v_add_u32_e32 v18, v18, v5
	s_waitcnt vmcnt(9)
	v_add_u32_e32 v18, v18, v6
	s_waitcnt vmcnt(8)
	v_add_u32_e32 v18, v18, v7
	s_waitcnt vmcnt(7)
	v_add_u32_e32 v18, v18, v8
	s_waitcnt vmcnt(6)
	v_add_u32_e32 v18, v18, v9
	s_waitcnt vmcnt(5)
	v_add_u32_e32 v18, v18, v10
	s_waitcnt vmcnt(4)
	v_add_u32_e32 v18, v18, v11
	s_waitcnt vmcnt(3)
	v_add_u32_e32 v18, v18, v12
	s_waitcnt vmcnt(2)
	v_add_u32_e32 v18, v18, v13
	s_waitcnt vmcnt(1)
	v_add_u32_e32 v18, v18, v14
	s_waitcnt vmcnt(0)
	v_add_u32_e32 v18, v18, v15
	v_cmp_eq_u32_e32 vcc, s33, v18
	s_cbranch_vccnz .LBB0_854
	s_and_b32 s38, s44, 0xff
	s_cmp_eq_u32 s38, 0
	s_mov_b64 s[38:39], -1
	s_mov_b64 s[42:43], -1
	s_sleep 8
	s_cbranch_scc1 .LBB0_859
	s_and_b64 vcc, exec, s[42:43]
	s_cbranch_vccz .LBB0_854
